# SwiGLU epilogues: 120 pairs of scalar v_mul(-log2e)/v_add(1.0) on aligned register pairs packed into v_pk_mul_f32/v_pk_add_f32
# speedup vs baseline: 1.0105x; 1.0105x over previous
.LBB0_74:
	s_add_u32 s42, s30, 0xfffc0080
	s_addc_u32 s43, s31, -1
	s_add_i32 s80, 0, 0x10000
	v_add_u32_e32 v140, s80, v144
	ds_read_b128 v[146:149], v140
	ds_read_b128 v[150:153], v140 offset:1024
	ds_read_b128 v[154:157], v140 offset:2048
	ds_read_b128 v[158:161], v140 offset:3072
	s_cmp_eq_u32 s79, 12
	s_cselect_b32 s53, s45, s43
	s_cselect_b32 s52, s75, s42
	s_cselect_b32 s51, s1, s78
	s_cselect_b32 s50, s76, s77
	v_lshl_add_u64 v[140:141], s[30:31], 0, v[136:137]
	s_add_i32 m0, s58, 0xc000
	ds_read_b128 v[166:169], v145
	ds_read_b128 v[174:177], v145 offset:1024
	ds_read_b128 v[178:181], v145 offset:2048
	ds_read_b128 v[182:185], v145 offset:3072
	ds_read_b128 v[186:189], v145 offset:4096
	ds_read_b128 v[190:193], v145 offset:5120
	ds_read_b128 v[194:197], v145 offset:6144
	ds_read_b128 v[198:201], v145 offset:7168
	global_load_lds_dwordx4 v[140:141], off
	v_lshl_add_u64 v[140:141], s[30:31], 0, v[138:139]
	s_add_i32 m0, s58, 0xe000
	s_nop 0
	global_load_lds_dwordx4 v[140:141], off
	s_waitcnt lgkmcnt(8)
	s_barrier
	s_waitcnt lgkmcnt(0)
	s_setprio 1
	s_waitcnt lgkmcnt(0)
	v_mfma_f32_16x16x32_bf16 v[126:129], v[146:149], v[166:169], v[126:129]
	v_mfma_f32_16x16x32_bf16 v[114:117], v[154:157], v[166:169], v[114:117]
	v_mfma_f32_16x16x32_bf16 v[110:113], v[146:149], v[178:181], v[110:113]
	v_mfma_f32_16x16x32_bf16 v[98:101], v[154:157], v[178:181], v[98:101]
	v_mfma_f32_16x16x32_bf16 v[92:95], v[146:149], v[186:189], v[92:95]
	v_mfma_f32_16x16x32_bf16 v[80:83], v[154:157], v[186:189], v[80:83]
	v_mfma_f32_16x16x32_bf16 v[76:79], v[146:149], v[194:197], v[76:79]
	v_mfma_f32_16x16x32_bf16 v[64:67], v[154:157], v[194:197], v[64:67]
	v_mfma_f32_16x16x32_bf16 v[126:129], v[150:153], v[174:177], v[126:129]
	v_mfma_f32_16x16x32_bf16 v[114:117], v[158:161], v[174:177], v[114:117]
	v_mfma_f32_16x16x32_bf16 v[110:113], v[150:153], v[182:185], v[110:113]
	v_mfma_f32_16x16x32_bf16 v[98:101], v[158:161], v[182:185], v[98:101]
	v_mfma_f32_16x16x32_bf16 v[92:95], v[150:153], v[190:193], v[92:95]
	v_mfma_f32_16x16x32_bf16 v[80:83], v[158:161], v[190:193], v[80:83]
	v_mfma_f32_16x16x32_bf16 v[76:79], v[150:153], v[198:201], v[76:79]
	v_mfma_f32_16x16x32_bf16 v[64:67], v[158:161], v[198:201], v[64:67]
	s_setprio 0
	s_barrier
	s_add_i32 s81, 0, 0x14000
	v_add_u32_e32 v140, s81, v144
	s_add_i32 s42, s80, s37
	ds_read_b128 v[206:209], v140
	ds_read_b128 v[216:219], v140 offset:1024
	ds_read_b128 v[220:223], v140 offset:2048
	ds_read_b128 v[224:227], v140 offset:3072
	v_lshl_add_u64 v[140:141], s[50:51], 0, v[96:97]
	s_mov_b32 m0, s42
	v_lshl_add_u64 v[162:163], s[50:51], 0, v[130:131]
	global_load_lds_dwordx4 v[140:141], off
	s_add_i32 m0, s42, 0x2000
	s_nop 0
	global_load_lds_dwordx4 v[162:163], off
	s_barrier
	s_waitcnt lgkmcnt(0)
	s_setprio 1
	s_waitcnt lgkmcnt(0)
	v_mfma_f32_16x16x32_bf16 v[122:125], v[206:209], v[166:169], v[122:125]
	v_mfma_f32_16x16x32_bf16 v[118:121], v[220:223], v[166:169], v[118:121]
	v_mfma_f32_16x16x32_bf16 v[106:109], v[206:209], v[178:181], v[106:109]
	v_mfma_f32_16x16x32_bf16 v[102:105], v[220:223], v[178:181], v[102:105]
	v_mfma_f32_16x16x32_bf16 v[88:91], v[206:209], v[186:189], v[88:91]
	v_mfma_f32_16x16x32_bf16 v[84:87], v[220:223], v[186:189], v[84:87]
	v_mfma_f32_16x16x32_bf16 v[72:75], v[206:209], v[194:197], v[72:75]
	v_mfma_f32_16x16x32_bf16 v[68:71], v[220:223], v[194:197], v[68:71]
	v_mfma_f32_16x16x32_bf16 v[122:125], v[216:219], v[174:177], v[122:125]
	v_mfma_f32_16x16x32_bf16 v[118:121], v[224:227], v[174:177], v[118:121]
	v_mfma_f32_16x16x32_bf16 v[106:109], v[216:219], v[182:185], v[106:109]
	v_mfma_f32_16x16x32_bf16 v[102:105], v[224:227], v[182:185], v[102:105]
	v_mfma_f32_16x16x32_bf16 v[88:91], v[216:219], v[190:193], v[88:91]
	v_mfma_f32_16x16x32_bf16 v[84:87], v[224:227], v[190:193], v[84:87]
	v_mfma_f32_16x16x32_bf16 v[72:75], v[216:219], v[198:201], v[72:75]
	v_mfma_f32_16x16x32_bf16 v[68:71], v[224:227], v[198:201], v[68:71]
	s_setprio 0
	s_mov_b32 m0, s58
	v_lshl_add_u64 v[164:165], s[52:53], 0, v[134:135]
	s_barrier
	ds_read_b128 v[166:169], v145 offset:16384
	ds_read_b128 v[174:177], v145 offset:17408
	ds_read_b128 v[178:181], v145 offset:18432
	ds_read_b128 v[182:185], v145 offset:19456
	ds_read_b128 v[186:189], v145 offset:20480
	ds_read_b128 v[190:193], v145 offset:21504
	ds_read_b128 v[194:197], v145 offset:22528
	ds_read_b128 v[198:201], v145 offset:23552
	global_load_lds_dwordx4 v[164:165], off
	v_lshl_add_u64 v[172:173], s[52:53], 0, v[132:133]
	s_mov_b32 m0, s59
	s_nop 0
	global_load_lds_dwordx4 v[172:173], off
	s_barrier
	s_waitcnt lgkmcnt(0)
	s_setprio 1
	s_waitcnt lgkmcnt(0)
	v_mfma_f32_16x16x32_bf16 v[60:63], v[146:149], v[166:169], v[60:63]
	v_mfma_f32_16x16x32_bf16 v[48:51], v[154:157], v[166:169], v[48:51]
	v_mfma_f32_16x16x32_bf16 v[44:47], v[146:149], v[178:181], v[44:47]
	v_mfma_f32_16x16x32_bf16 v[32:35], v[154:157], v[178:181], v[32:35]
	v_mfma_f32_16x16x32_bf16 v[28:31], v[146:149], v[186:189], v[28:31]
	v_mfma_f32_16x16x32_bf16 v[16:19], v[154:157], v[186:189], v[16:19]
	v_mfma_f32_16x16x32_bf16 v[12:15], v[146:149], v[194:197], v[12:15]
	v_mfma_f32_16x16x32_bf16 v[4:7], v[154:157], v[194:197], v[4:7]
	v_mfma_f32_16x16x32_bf16 v[60:63], v[150:153], v[174:177], v[60:63]
	v_mfma_f32_16x16x32_bf16 v[48:51], v[158:161], v[174:177], v[48:51]
	v_mfma_f32_16x16x32_bf16 v[44:47], v[150:153], v[182:185], v[44:47]
	v_mfma_f32_16x16x32_bf16 v[32:35], v[158:161], v[182:185], v[32:35]
	v_mfma_f32_16x16x32_bf16 v[28:31], v[150:153], v[190:193], v[28:31]
	v_mfma_f32_16x16x32_bf16 v[16:19], v[158:161], v[190:193], v[16:19]
	v_mfma_f32_16x16x32_bf16 v[12:15], v[150:153], v[198:201], v[12:15]
	v_mfma_f32_16x16x32_bf16 v[4:7], v[158:161], v[198:201], v[4:7]
	s_setprio 0
	s_barrier
	s_add_u32 s42, s50, 0x40000
	s_addc_u32 s43, s51, 0
	s_add_i32 s80, s81, s37
	v_lshl_add_u64 v[146:147], s[42:43], 0, v[96:97]
	s_mov_b32 m0, s80
	s_nop 0
	global_load_lds_dwordx4 v[146:147], off
	v_lshl_add_u64 v[146:147], s[42:43], 0, v[130:131]
	s_add_i32 m0, s80, 0x2000
	s_nop 0
	global_load_lds_dwordx4 v[146:147], off
	s_waitcnt vmcnt(6)
	s_barrier
	s_setprio 1
	v_mfma_f32_16x16x32_bf16 v[56:59], v[206:209], v[166:169], v[56:59]
	v_mfma_f32_16x16x32_bf16 v[52:55], v[220:223], v[166:169], v[52:55]
	v_mfma_f32_16x16x32_bf16 v[40:43], v[206:209], v[178:181], v[40:43]
	v_mfma_f32_16x16x32_bf16 v[36:39], v[220:223], v[178:181], v[36:39]
	v_mfma_f32_16x16x32_bf16 v[24:27], v[206:209], v[186:189], v[24:27]
	v_mfma_f32_16x16x32_bf16 v[20:23], v[220:223], v[186:189], v[20:23]
	v_mfma_f32_16x16x32_bf16 v[8:11], v[206:209], v[194:197], v[8:11]
	v_mfma_f32_16x16x32_bf16 v[0:3], v[220:223], v[194:197], v[0:3]
	v_mfma_f32_16x16x32_bf16 v[56:59], v[216:219], v[174:177], v[56:59]
	v_mfma_f32_16x16x32_bf16 v[52:55], v[224:227], v[174:177], v[52:55]
	v_mfma_f32_16x16x32_bf16 v[40:43], v[216:219], v[182:185], v[40:43]
	v_mfma_f32_16x16x32_bf16 v[36:39], v[224:227], v[182:185], v[36:39]
	v_mfma_f32_16x16x32_bf16 v[24:27], v[216:219], v[190:193], v[24:27]
	v_mfma_f32_16x16x32_bf16 v[20:23], v[224:227], v[190:193], v[20:23]
	v_mfma_f32_16x16x32_bf16 v[8:11], v[216:219], v[198:201], v[8:11]
	v_mfma_f32_16x16x32_bf16 v[0:3], v[224:227], v[198:201], v[0:3]
	s_setprio 0
	s_add_i32 s80, 0, 0x18000
	v_add_u32_e32 v158, s80, v144
	s_barrier
	ds_read_b128 v[146:149], v158
	ds_read_b128 v[150:153], v158 offset:1024
	ds_read_b128 v[154:157], v158 offset:2048
	ds_read_b128 v[158:161], v158 offset:3072
	s_add_u32 s42, s52, 0x40000
	s_addc_u32 s43, s53, 0
	s_mov_b32 m0, s60
	v_lshl_add_u64 v[202:203], s[42:43], 0, v[134:135]
	ds_read_b128 v[166:169], v145 offset:32768
	ds_read_b128 v[174:177], v145 offset:33792
	ds_read_b128 v[178:181], v145 offset:34816
	ds_read_b128 v[182:185], v145 offset:35840
	ds_read_b128 v[186:189], v145 offset:36864
	ds_read_b128 v[190:193], v145 offset:37888
	ds_read_b128 v[194:197], v145 offset:38912
	ds_read_b128 v[198:201], v145 offset:39936
	global_load_lds_dwordx4 v[202:203], off
	v_lshl_add_u64 v[202:203], s[42:43], 0, v[132:133]
	s_mov_b32 m0, s61
	s_nop 0
	global_load_lds_dwordx4 v[202:203], off
	s_waitcnt lgkmcnt(8)
	s_barrier
	s_waitcnt lgkmcnt(0)
	s_setprio 1
	s_waitcnt lgkmcnt(0)
	v_mfma_f32_16x16x32_bf16 v[126:129], v[146:149], v[166:169], v[126:129]
	v_mfma_f32_16x16x32_bf16 v[114:117], v[154:157], v[166:169], v[114:117]
	v_mfma_f32_16x16x32_bf16 v[110:113], v[146:149], v[178:181], v[110:113]
	v_mfma_f32_16x16x32_bf16 v[98:101], v[154:157], v[178:181], v[98:101]
	v_mfma_f32_16x16x32_bf16 v[92:95], v[146:149], v[186:189], v[92:95]
	v_mfma_f32_16x16x32_bf16 v[80:83], v[154:157], v[186:189], v[80:83]
	v_mfma_f32_16x16x32_bf16 v[76:79], v[146:149], v[194:197], v[76:79]
	v_mfma_f32_16x16x32_bf16 v[64:67], v[154:157], v[194:197], v[64:67]
	v_mfma_f32_16x16x32_bf16 v[126:129], v[150:153], v[174:177], v[126:129]
	v_mfma_f32_16x16x32_bf16 v[114:117], v[158:161], v[174:177], v[114:117]
	v_mfma_f32_16x16x32_bf16 v[110:113], v[150:153], v[182:185], v[110:113]
	v_mfma_f32_16x16x32_bf16 v[98:101], v[158:161], v[182:185], v[98:101]
	v_mfma_f32_16x16x32_bf16 v[92:95], v[150:153], v[190:193], v[92:95]
	v_mfma_f32_16x16x32_bf16 v[80:83], v[158:161], v[190:193], v[80:83]
	v_mfma_f32_16x16x32_bf16 v[76:79], v[150:153], v[198:201], v[76:79]
	v_mfma_f32_16x16x32_bf16 v[64:67], v[158:161], v[198:201], v[64:67]
	s_setprio 0
	s_barrier
	s_add_i32 s52, 0, 0x1c000
	s_add_i32 s42, s80, s37
	v_add_u32_e32 v171, s52, v144
	v_lshl_add_u64 v[140:141], v[140:141], 0, s[56:57]
	s_mov_b32 m0, s42
	ds_read_b128 v[206:209], v171
	ds_read_b128 v[216:219], v171 offset:1024
	ds_read_b128 v[220:223], v171 offset:2048
	ds_read_b128 v[224:227], v171 offset:3072
	global_load_lds_dwordx4 v[140:141], off
	v_lshl_add_u64 v[140:141], v[162:163], 0, s[56:57]
	s_add_i32 m0, s42, 0x2000
	s_nop 0
	global_load_lds_dwordx4 v[140:141], off
	s_barrier
	s_waitcnt lgkmcnt(0)
	s_setprio 1
	s_waitcnt lgkmcnt(0)
	v_mfma_f32_16x16x32_bf16 v[122:125], v[206:209], v[166:169], v[122:125]
	v_mfma_f32_16x16x32_bf16 v[118:121], v[220:223], v[166:169], v[118:121]
	v_mfma_f32_16x16x32_bf16 v[106:109], v[206:209], v[178:181], v[106:109]
	v_mfma_f32_16x16x32_bf16 v[102:105], v[220:223], v[178:181], v[102:105]
	v_mfma_f32_16x16x32_bf16 v[88:91], v[206:209], v[186:189], v[88:91]
	v_mfma_f32_16x16x32_bf16 v[84:87], v[220:223], v[186:189], v[84:87]
	v_mfma_f32_16x16x32_bf16 v[72:75], v[206:209], v[194:197], v[72:75]
	v_mfma_f32_16x16x32_bf16 v[68:71], v[220:223], v[194:197], v[68:71]
	v_mfma_f32_16x16x32_bf16 v[122:125], v[216:219], v[174:177], v[122:125]
	v_mfma_f32_16x16x32_bf16 v[118:121], v[224:227], v[174:177], v[118:121]
	v_mfma_f32_16x16x32_bf16 v[106:109], v[216:219], v[182:185], v[106:109]
	v_mfma_f32_16x16x32_bf16 v[102:105], v[224:227], v[182:185], v[102:105]
	v_mfma_f32_16x16x32_bf16 v[88:91], v[216:219], v[190:193], v[88:91]
	v_mfma_f32_16x16x32_bf16 v[84:87], v[224:227], v[190:193], v[84:87]
	v_mfma_f32_16x16x32_bf16 v[72:75], v[216:219], v[198:201], v[72:75]
	v_mfma_f32_16x16x32_bf16 v[68:71], v[224:227], v[198:201], v[68:71]
	s_setprio 0
	s_mov_b32 m0, s70
	v_lshl_add_u64 v[140:141], v[164:165], 0, s[56:57]
	s_barrier
	ds_read_b128 v[166:169], v145 offset:49152
	ds_read_b128 v[174:177], v145 offset:50176
	ds_read_b128 v[178:181], v145 offset:51200
	ds_read_b128 v[182:185], v145 offset:52224
	ds_read_b128 v[186:189], v145 offset:53248
	ds_read_b128 v[190:193], v145 offset:54272
	ds_read_b128 v[194:197], v145 offset:55296
	ds_read_b128 v[198:201], v145 offset:56320
	global_load_lds_dwordx4 v[140:141], off
	v_lshl_add_u64 v[140:141], v[172:173], 0, s[56:57]
	s_mov_b32 m0, s71
	s_nop 0
	global_load_lds_dwordx4 v[140:141], off
	s_barrier
	s_waitcnt lgkmcnt(0)
	s_setprio 1
	s_waitcnt lgkmcnt(0)
	v_mfma_f32_16x16x32_bf16 v[60:63], v[146:149], v[166:169], v[60:63]
	v_mfma_f32_16x16x32_bf16 v[48:51], v[154:157], v[166:169], v[48:51]
	v_mfma_f32_16x16x32_bf16 v[44:47], v[146:149], v[178:181], v[44:47]
	v_mfma_f32_16x16x32_bf16 v[32:35], v[154:157], v[178:181], v[32:35]
	v_mfma_f32_16x16x32_bf16 v[28:31], v[146:149], v[186:189], v[28:31]
	v_mfma_f32_16x16x32_bf16 v[16:19], v[154:157], v[186:189], v[16:19]
	v_mfma_f32_16x16x32_bf16 v[12:15], v[146:149], v[194:197], v[12:15]
	v_mfma_f32_16x16x32_bf16 v[4:7], v[154:157], v[194:197], v[4:7]
	v_mfma_f32_16x16x32_bf16 v[60:63], v[150:153], v[174:177], v[60:63]
	v_mfma_f32_16x16x32_bf16 v[48:51], v[158:161], v[174:177], v[48:51]
	v_mfma_f32_16x16x32_bf16 v[44:47], v[150:153], v[182:185], v[44:47]
	v_mfma_f32_16x16x32_bf16 v[32:35], v[158:161], v[182:185], v[32:35]
	v_mfma_f32_16x16x32_bf16 v[28:31], v[150:153], v[190:193], v[28:31]
	v_mfma_f32_16x16x32_bf16 v[16:19], v[158:161], v[190:193], v[16:19]
	v_mfma_f32_16x16x32_bf16 v[12:15], v[150:153], v[198:201], v[12:15]
	v_mfma_f32_16x16x32_bf16 v[4:7], v[158:161], v[198:201], v[4:7]
	s_setprio 0
	s_barrier
	s_add_u32 s42, s50, 0x40080
	s_addc_u32 s43, s51, 0
	s_add_i32 s50, s52, s37
	v_lshl_add_u64 v[140:141], s[42:43], 0, v[96:97]
	s_mov_b32 m0, s50
	s_nop 0
	global_load_lds_dwordx4 v[140:141], off
	v_lshl_add_u64 v[140:141], s[42:43], 0, v[130:131]
	s_add_i32 m0, s50, 0x2000
	s_nop 0
	global_load_lds_dwordx4 v[140:141], off
	s_waitcnt vmcnt(6)
	s_barrier
	s_setprio 1
	v_mfma_f32_16x16x32_bf16 v[56:59], v[206:209], v[166:169], v[56:59]
	v_mfma_f32_16x16x32_bf16 v[52:55], v[220:223], v[166:169], v[52:55]
	v_mfma_f32_16x16x32_bf16 v[40:43], v[206:209], v[178:181], v[40:43]
	v_mfma_f32_16x16x32_bf16 v[36:39], v[220:223], v[178:181], v[36:39]
	v_mfma_f32_16x16x32_bf16 v[24:27], v[206:209], v[186:189], v[24:27]
	v_mfma_f32_16x16x32_bf16 v[20:23], v[220:223], v[186:189], v[20:23]
	v_mfma_f32_16x16x32_bf16 v[8:11], v[206:209], v[194:197], v[8:11]
	v_mfma_f32_16x16x32_bf16 v[0:3], v[220:223], v[194:197], v[0:3]
	v_mfma_f32_16x16x32_bf16 v[56:59], v[216:219], v[174:177], v[56:59]
	v_mfma_f32_16x16x32_bf16 v[52:55], v[224:227], v[174:177], v[52:55]
	v_mfma_f32_16x16x32_bf16 v[40:43], v[216:219], v[182:185], v[40:43]
	v_mfma_f32_16x16x32_bf16 v[36:39], v[224:227], v[182:185], v[36:39]
	v_mfma_f32_16x16x32_bf16 v[24:27], v[216:219], v[190:193], v[24:27]
	v_mfma_f32_16x16x32_bf16 v[20:23], v[224:227], v[190:193], v[20:23]
	v_mfma_f32_16x16x32_bf16 v[8:11], v[216:219], v[198:201], v[8:11]
	v_mfma_f32_16x16x32_bf16 v[0:3], v[224:227], v[198:201], v[0:3]
	s_setprio 0
	s_add_i32 s79, s79, 2
	s_add_u32 s30, s30, 0x100
	s_addc_u32 s31, s31, 0
	s_add_u32 s77, s77, 0x100
	s_addc_u32 s78, s78, 0
	s_cmp_gt_u32 s79, 13
	s_barrier
	s_cbranch_scc0 .LBB0_74
	v_mov_b32_e32 v174, 0xbfb8aa3b
	v_mul_f32_e32 v147, 0xbfb8aa3b, v126
	v_exp_f32_e32 v147, v147
	v_pk_mul_f32 v[122:123], v[126:127], v[122:123]
	v_mul_f32_e32 v126, 0xbfb8aa3b, v128
	v_exp_f32_e32 v126, v126
	v_add_f32_e32 v147, 1.0, v147
	v_rcp_f32_e32 v152, v147
	v_mul_f32_e32 v147, 0xbfb8aa3b, v127
	v_mul_f32_e32 v127, 0xbfb8aa3b, v129
	v_exp_f32_e32 v127, v127
	v_add_f32_e32 v126, 1.0, v126
	v_rcp_f32_e32 v126, v126
	v_pk_mul_f32 v[124:125], v[128:129], v[124:125]
	v_add_f32_e32 v127, 1.0, v127
	v_rcp_f32_e32 v127, v127
	v_exp_f32_e32 v147, v147
	s_lshl_b32 s30, s73, 7
	v_mov_b32_e32 v140, v143
	v_pk_mul_f32 v[124:125], v[126:127], v[124:125]
	v_pk_mul_f32 v[126:127], v[114:115], v[174:175] op_sel_hi:[1,0]
	v_exp_f32_e32 v126, v126
	v_exp_f32_e32 v127, v127
	v_pk_mul_f32 v[114:115], v[114:115], v[118:119]
	v_add_f32_e32 v147, 1.0, v147
	v_pk_add_f32 v[126:127], v[126:127], 1.0 op_sel_hi:[1,0]
	v_rcp_f32_e32 v126, v126
	v_rcp_f32_e32 v127, v127
	v_mov_b32_e32 v141, v142
	s_or_b32 s30, s30, s69
	v_rcp_f32_e32 v153, v147
	v_pk_mul_f32 v[118:119], v[126:127], v[114:115]
	v_pk_mul_f32 v[114:115], v[116:117], v[174:175] op_sel_hi:[1,0]
	v_exp_f32_e32 v114, v114
	v_exp_f32_e32 v115, v115
	s_lshl_b32 s1, s74, 8
	v_pk_add_f32 v[114:115], v[114:115], 1.0 op_sel_hi:[1,0]
	v_rcp_f32_e32 v114, v114
	v_rcp_f32_e32 v115, v115
	v_lshl_add_u32 v148, v140, 3, s30
	v_readlane_b32 s30, v254, 11
	s_add_i32 s1, s1, s68
	v_readlane_b32 s31, v254, 12
	v_add_u32_e32 v146, s1, v141
	v_ashrrev_i32_e32 v149, 31, v148
	v_mov_b64_e32 v[140:141], s[30:31]
	s_movk_i32 s1, 0x1600
	v_pk_mul_f32 v[120:121], v[116:117], v[120:121]
	v_mad_i64_i32 v[150:151], s[30:31], v146, s1, v[140:141]
	v_pk_mul_f32 v[122:123], v[152:153], v[122:123]
	v_pk_mul_f32 v[120:121], v[114:115], v[120:121]
	v_lshlrev_b64 v[114:115], 1, v[148:149]
	v_lshl_add_u64 v[126:127], v[150:151], 0, v[114:115]
	v_cvt_pk_bf16_f32 v116, v122, v123
	v_cvt_pk_bf16_f32 v117, v124, v125
	v_cvt_pk_bf16_f32 v118, v118, v119
	v_cvt_pk_bf16_f32 v119, v120, v121
	global_store_dwordx4 v[126:127], v[116:119], off
	v_pk_mul_f32 v[106:107], v[110:111], v[106:107]
	v_pk_mul_f32 v[108:109], v[112:113], v[108:109]
	v_pk_mul_f32 v[118:119], v[110:111], v[174:175] op_sel_hi:[1,0]
	v_pk_mul_f32 v[110:111], v[112:113], v[174:175] op_sel_hi:[1,0]
	v_exp_f32_e32 v110, v110
	v_exp_f32_e32 v111, v111
	v_exp_f32_e32 v118, v118
	v_exp_f32_e32 v119, v119
	v_pk_add_f32 v[110:111], v[110:111], 1.0 op_sel_hi:[1,0]
	v_rcp_f32_e32 v110, v110
	v_rcp_f32_e32 v111, v111
	v_pk_add_f32 v[118:119], v[118:119], 1.0 op_sel_hi:[1,0]
	v_rcp_f32_e32 v118, v118
	v_pk_mul_f32 v[108:109], v[110:111], v[108:109]
	v_pk_mul_f32 v[110:111], v[98:99], v[174:175] op_sel_hi:[1,0]
	v_exp_f32_e32 v110, v110
	v_exp_f32_e32 v111, v111
	v_pk_mul_f32 v[98:99], v[98:99], v[102:103]
	v_rcp_f32_e32 v119, v119
	v_pk_add_f32 v[110:111], v[110:111], 1.0 op_sel_hi:[1,0]
	v_rcp_f32_e32 v110, v110
	v_rcp_f32_e32 v111, v111
	v_add_u32_e32 v116, 16, v146
	v_pk_mul_f32 v[104:105], v[100:101], v[104:105]
	v_mad_i64_i32 v[116:117], s[30:31], v116, s1, v[140:141]
	v_pk_mul_f32 v[102:103], v[110:111], v[98:99]
	v_pk_mul_f32 v[98:99], v[100:101], v[174:175] op_sel_hi:[1,0]
	v_exp_f32_e32 v98, v98
	v_exp_f32_e32 v99, v99
	v_pk_mul_f32 v[106:107], v[118:119], v[106:107]
	v_lshl_add_u64 v[110:111], v[116:117], 0, v[114:115]
	v_pk_add_f32 v[98:99], v[98:99], 1.0 op_sel_hi:[1,0]
	v_rcp_f32_e32 v98, v98
	v_rcp_f32_e32 v99, v99
	v_cvt_pk_bf16_f32 v100, v102, v103
	v_pk_mul_f32 v[88:89], v[92:93], v[88:89]
	v_pk_mul_f32 v[90:91], v[94:95], v[90:91]
	v_pk_mul_f32 v[104:105], v[98:99], v[104:105]
	v_cvt_pk_bf16_f32 v98, v106, v107
	v_cvt_pk_bf16_f32 v99, v108, v109
	v_cvt_pk_bf16_f32 v101, v104, v105
	global_store_dwordx4 v[110:111], v[98:101], off
	v_pk_mul_f32 v[86:87], v[82:83], v[86:87]
	v_pk_mul_f32 v[72:73], v[76:77], v[72:73]
	v_pk_mul_f32 v[100:101], v[92:93], v[174:175] op_sel_hi:[1,0]
	v_pk_mul_f32 v[92:93], v[94:95], v[174:175] op_sel_hi:[1,0]
	v_exp_f32_e32 v92, v92
	v_exp_f32_e32 v93, v93
	v_exp_f32_e32 v100, v100
	v_exp_f32_e32 v101, v101
	v_pk_add_f32 v[92:93], v[92:93], 1.0 op_sel_hi:[1,0]
	v_rcp_f32_e32 v92, v92
	v_rcp_f32_e32 v93, v93
	v_pk_add_f32 v[100:101], v[100:101], 1.0 op_sel_hi:[1,0]
	v_rcp_f32_e32 v100, v100
	v_pk_mul_f32 v[90:91], v[92:93], v[90:91]
	v_pk_mul_f32 v[92:93], v[80:81], v[174:175] op_sel_hi:[1,0]
	v_exp_f32_e32 v92, v92
	v_exp_f32_e32 v93, v93
	v_pk_mul_f32 v[80:81], v[80:81], v[84:85]
	v_rcp_f32_e32 v101, v101
	v_pk_add_f32 v[92:93], v[92:93], 1.0 op_sel_hi:[1,0]
	v_rcp_f32_e32 v92, v92
	v_rcp_f32_e32 v93, v93
	v_add_u32_e32 v98, 32, v146
	v_mad_i64_i32 v[98:99], s[30:31], v98, s1, v[140:141]
	v_pk_mul_f32 v[84:85], v[92:93], v[80:81]
	v_pk_mul_f32 v[80:81], v[82:83], v[174:175] op_sel_hi:[1,0]
	v_exp_f32_e32 v80, v80
	v_exp_f32_e32 v81, v81
	v_pk_mul_f32 v[88:89], v[100:101], v[88:89]
	v_lshl_add_u64 v[92:93], v[98:99], 0, v[114:115]
	v_pk_add_f32 v[80:81], v[80:81], 1.0 op_sel_hi:[1,0]
	v_rcp_f32_e32 v80, v80
	v_rcp_f32_e32 v81, v81
	v_cvt_pk_bf16_f32 v82, v84, v85
	v_pk_mul_f32 v[74:75], v[78:79], v[74:75]
	v_pk_mul_f32 v[70:71], v[66:67], v[70:71]
	v_pk_mul_f32 v[86:87], v[80:81], v[86:87]
	v_cvt_pk_bf16_f32 v80, v88, v89
	v_cvt_pk_bf16_f32 v81, v90, v91
	v_cvt_pk_bf16_f32 v83, v86, v87
	global_store_dwordx4 v[92:93], v[80:83], off
	v_pk_mul_f32 v[56:57], v[60:61], v[56:57]
	v_pk_mul_f32 v[58:59], v[62:63], v[58:59]
	v_pk_mul_f32 v[82:83], v[76:77], v[174:175] op_sel_hi:[1,0]
	v_pk_mul_f32 v[76:77], v[78:79], v[174:175] op_sel_hi:[1,0]
	v_exp_f32_e32 v76, v76
	v_exp_f32_e32 v77, v77
	v_exp_f32_e32 v82, v82
	v_exp_f32_e32 v83, v83
	v_pk_add_f32 v[76:77], v[76:77], 1.0 op_sel_hi:[1,0]
	v_rcp_f32_e32 v76, v76
	v_rcp_f32_e32 v77, v77
	v_pk_add_f32 v[82:83], v[82:83], 1.0 op_sel_hi:[1,0]
	v_rcp_f32_e32 v82, v82
	v_pk_mul_f32 v[74:75], v[76:77], v[74:75]
	v_pk_mul_f32 v[76:77], v[64:65], v[174:175] op_sel_hi:[1,0]
	v_exp_f32_e32 v76, v76
	v_exp_f32_e32 v77, v77
	v_pk_mul_f32 v[64:65], v[64:65], v[68:69]
	v_rcp_f32_e32 v83, v83
	v_pk_add_f32 v[76:77], v[76:77], 1.0 op_sel_hi:[1,0]
	v_rcp_f32_e32 v76, v76
	v_rcp_f32_e32 v77, v77
	v_add_u32_e32 v80, 48, v146
	v_mad_i64_i32 v[80:81], s[30:31], v80, s1, v[140:141]
	v_pk_mul_f32 v[68:69], v[76:77], v[64:65]
	v_pk_mul_f32 v[64:65], v[66:67], v[174:175] op_sel_hi:[1,0]
	v_exp_f32_e32 v64, v64
	v_exp_f32_e32 v65, v65
	v_pk_mul_f32 v[72:73], v[82:83], v[72:73]
	v_lshl_add_u64 v[76:77], v[80:81], 0, v[114:115]
	v_pk_add_f32 v[64:65], v[64:65], 1.0 op_sel_hi:[1,0]
	v_rcp_f32_e32 v64, v64
	v_rcp_f32_e32 v65, v65
	v_cvt_pk_bf16_f32 v66, v68, v69
	v_pk_mul_f32 v[54:55], v[50:51], v[54:55]
	v_pk_mul_f32 v[40:41], v[44:45], v[40:41]
	v_pk_mul_f32 v[70:71], v[64:65], v[70:71]
	v_cvt_pk_bf16_f32 v64, v72, v73
	v_cvt_pk_bf16_f32 v65, v74, v75
	v_cvt_pk_bf16_f32 v67, v70, v71
	global_store_dwordx4 v[76:77], v[64:67], off
	v_pk_mul_f32 v[42:43], v[46:47], v[42:43]
	v_pk_mul_f32 v[38:39], v[34:35], v[38:39]
	v_pk_mul_f32 v[66:67], v[60:61], v[174:175] op_sel_hi:[1,0]
	v_pk_mul_f32 v[60:61], v[62:63], v[174:175] op_sel_hi:[1,0]
	v_exp_f32_e32 v60, v60
	v_exp_f32_e32 v61, v61
	v_exp_f32_e32 v66, v66
	v_exp_f32_e32 v67, v67
	v_pk_add_f32 v[60:61], v[60:61], 1.0 op_sel_hi:[1,0]
	v_rcp_f32_e32 v60, v60
	v_rcp_f32_e32 v61, v61
	v_pk_add_f32 v[66:67], v[66:67], 1.0 op_sel_hi:[1,0]
	v_rcp_f32_e32 v66, v66
	v_pk_mul_f32 v[58:59], v[60:61], v[58:59]
	v_pk_mul_f32 v[60:61], v[48:49], v[174:175] op_sel_hi:[1,0]
	v_exp_f32_e32 v60, v60
	v_exp_f32_e32 v61, v61
	v_pk_mul_f32 v[48:49], v[48:49], v[52:53]
	v_rcp_f32_e32 v67, v67
	v_pk_add_f32 v[60:61], v[60:61], 1.0 op_sel_hi:[1,0]
	v_rcp_f32_e32 v60, v60
	v_rcp_f32_e32 v61, v61
	v_add_u32_e32 v64, 0x80, v146
	v_mad_i64_i32 v[64:65], s[30:31], v64, s1, v[140:141]
	v_pk_mul_f32 v[52:53], v[60:61], v[48:49]
	v_pk_mul_f32 v[48:49], v[50:51], v[174:175] op_sel_hi:[1,0]
	v_exp_f32_e32 v48, v48
	v_exp_f32_e32 v49, v49
	v_pk_mul_f32 v[56:57], v[66:67], v[56:57]
	v_lshl_add_u64 v[60:61], v[64:65], 0, v[114:115]
	v_pk_add_f32 v[48:49], v[48:49], 1.0 op_sel_hi:[1,0]
	v_rcp_f32_e32 v48, v48
	v_rcp_f32_e32 v49, v49
	v_cvt_pk_bf16_f32 v50, v52, v53
	v_pk_mul_f32 v[24:25], v[28:29], v[24:25]
	v_pk_mul_f32 v[26:27], v[30:31], v[26:27]
	v_pk_mul_f32 v[54:55], v[48:49], v[54:55]
	v_cvt_pk_bf16_f32 v48, v56, v57
	v_cvt_pk_bf16_f32 v49, v58, v59
	v_cvt_pk_bf16_f32 v51, v54, v55
	global_store_dwordx4 v[60:61], v[48:51], off
	v_pk_mul_f32 v[22:23], v[18:19], v[22:23]
	v_pk_mul_f32 v[8:9], v[12:13], v[8:9]
	v_pk_mul_f32 v[50:51], v[44:45], v[174:175] op_sel_hi:[1,0]
	v_pk_mul_f32 v[44:45], v[46:47], v[174:175] op_sel_hi:[1,0]
	v_exp_f32_e32 v44, v44
	v_exp_f32_e32 v45, v45
	v_exp_f32_e32 v50, v50
	v_exp_f32_e32 v51, v51
	v_pk_add_f32 v[44:45], v[44:45], 1.0 op_sel_hi:[1,0]
	v_rcp_f32_e32 v44, v44
	v_rcp_f32_e32 v45, v45
	v_pk_add_f32 v[50:51], v[50:51], 1.0 op_sel_hi:[1,0]
	v_rcp_f32_e32 v50, v50
	v_pk_mul_f32 v[42:43], v[44:45], v[42:43]
	v_pk_mul_f32 v[44:45], v[32:33], v[174:175] op_sel_hi:[1,0]
	v_exp_f32_e32 v44, v44
	v_exp_f32_e32 v45, v45
	v_pk_mul_f32 v[32:33], v[32:33], v[36:37]
	v_rcp_f32_e32 v51, v51
	v_pk_add_f32 v[44:45], v[44:45], 1.0 op_sel_hi:[1,0]
	v_rcp_f32_e32 v44, v44
	v_rcp_f32_e32 v45, v45
	v_add_u32_e32 v48, 0x90, v146
	v_mad_i64_i32 v[48:49], s[30:31], v48, s1, v[140:141]
	v_pk_mul_f32 v[36:37], v[44:45], v[32:33]
	v_pk_mul_f32 v[32:33], v[34:35], v[174:175] op_sel_hi:[1,0]
	v_exp_f32_e32 v32, v32
	v_exp_f32_e32 v33, v33
	v_pk_mul_f32 v[40:41], v[50:51], v[40:41]
	v_lshl_add_u64 v[44:45], v[48:49], 0, v[114:115]
	v_pk_add_f32 v[32:33], v[32:33], 1.0 op_sel_hi:[1,0]
	v_rcp_f32_e32 v32, v32
	v_rcp_f32_e32 v33, v33
	v_cvt_pk_bf16_f32 v34, v36, v37
	v_pk_mul_f32 v[10:11], v[14:15], v[10:11]
	v_pk_mul_f32 v[0:1], v[4:5], v[0:1]
	v_pk_mul_f32 v[38:39], v[32:33], v[38:39]
	v_cvt_pk_bf16_f32 v32, v40, v41
	v_cvt_pk_bf16_f32 v33, v42, v43
	v_cvt_pk_bf16_f32 v35, v38, v39
	global_store_dwordx4 v[44:45], v[32:35], off
	v_pk_mul_f32 v[2:3], v[6:7], v[2:3]
	s_and_b64 vcc, exec, s[40:41]
	v_pk_mul_f32 v[34:35], v[28:29], v[174:175] op_sel_hi:[1,0]
	v_pk_mul_f32 v[28:29], v[30:31], v[174:175] op_sel_hi:[1,0]
	v_exp_f32_e32 v28, v28
	v_exp_f32_e32 v29, v29
	v_exp_f32_e32 v34, v34
	v_exp_f32_e32 v35, v35
	v_pk_add_f32 v[28:29], v[28:29], 1.0 op_sel_hi:[1,0]
	v_rcp_f32_e32 v28, v28
	v_rcp_f32_e32 v29, v29
	v_pk_add_f32 v[34:35], v[34:35], 1.0 op_sel_hi:[1,0]
	v_rcp_f32_e32 v34, v34
	v_pk_mul_f32 v[26:27], v[28:29], v[26:27]
	v_pk_mul_f32 v[28:29], v[16:17], v[174:175] op_sel_hi:[1,0]
	v_exp_f32_e32 v28, v28
	v_exp_f32_e32 v29, v29
	v_pk_mul_f32 v[16:17], v[16:17], v[20:21]
	v_rcp_f32_e32 v35, v35
	v_pk_add_f32 v[28:29], v[28:29], 1.0 op_sel_hi:[1,0]
	v_rcp_f32_e32 v28, v28
	v_rcp_f32_e32 v29, v29
	v_add_u32_e32 v32, 0xa0, v146
	v_mad_i64_i32 v[32:33], s[30:31], v32, s1, v[140:141]
	v_pk_mul_f32 v[20:21], v[28:29], v[16:17]
	v_pk_mul_f32 v[16:17], v[18:19], v[174:175] op_sel_hi:[1,0]
	v_exp_f32_e32 v16, v16
	v_exp_f32_e32 v17, v17
	v_pk_mul_f32 v[24:25], v[34:35], v[24:25]
	v_lshl_add_u64 v[28:29], v[32:33], 0, v[114:115]
	v_pk_add_f32 v[16:17], v[16:17], 1.0 op_sel_hi:[1,0]
	v_rcp_f32_e32 v16, v16
	v_rcp_f32_e32 v17, v17
	v_cvt_pk_bf16_f32 v18, v20, v21
	s_mov_b32 s73, s0
	s_mov_b32 s74, s44
	v_pk_mul_f32 v[22:23], v[16:17], v[22:23]
	v_cvt_pk_bf16_f32 v16, v24, v25
	v_cvt_pk_bf16_f32 v17, v26, v27
	v_cvt_pk_bf16_f32 v19, v22, v23
	global_store_dwordx4 v[28:29], v[16:19], off
	s_mov_b64 s[50:51], s[48:49]
	s_nop 0
	v_pk_mul_f32 v[18:19], v[12:13], v[174:175] op_sel_hi:[1,0]
	v_pk_mul_f32 v[12:13], v[14:15], v[174:175] op_sel_hi:[1,0]
	v_exp_f32_e32 v12, v12
	v_exp_f32_e32 v13, v13
	v_exp_f32_e32 v18, v18
	v_exp_f32_e32 v19, v19
	v_pk_add_f32 v[12:13], v[12:13], 1.0 op_sel_hi:[1,0]
	v_rcp_f32_e32 v12, v12
	v_rcp_f32_e32 v13, v13
	v_pk_add_f32 v[18:19], v[18:19], 1.0 op_sel_hi:[1,0]
	v_rcp_f32_e32 v18, v18
	v_pk_mul_f32 v[10:11], v[12:13], v[10:11]
	v_pk_mul_f32 v[12:13], v[4:5], v[174:175] op_sel_hi:[1,0]
	v_exp_f32_e32 v12, v12
	v_exp_f32_e32 v13, v13
	v_rcp_f32_e32 v19, v19
	v_add_u32_e32 v16, 0xb0, v146
	v_pk_add_f32 v[12:13], v[12:13], 1.0 op_sel_hi:[1,0]
	v_rcp_f32_e32 v12, v12
	v_rcp_f32_e32 v13, v13
	v_mad_i64_i32 v[16:17], s[30:31], v16, s1, v[140:141]
	v_pk_mul_f32 v[8:9], v[18:19], v[8:9]
	v_pk_mul_f32 v[4:5], v[12:13], v[0:1]
	v_pk_mul_f32 v[0:1], v[6:7], v[174:175] op_sel_hi:[1,0]
	v_exp_f32_e32 v0, v0
	v_exp_f32_e32 v1, v1
	v_lshl_add_u64 v[12:13], v[16:17], 0, v[114:115]
	s_mov_b64 s[30:31], s[46:47]
	v_pk_add_f32 v[0:1], v[0:1], 1.0 op_sel_hi:[1,0]
	v_rcp_f32_e32 v0, v0
	v_rcp_f32_e32 v1, v1
	s_nop 0
	v_pk_mul_f32 v[6:7], v[0:1], v[2:3]
	v_cvt_pk_bf16_f32 v0, v8, v9
	v_cvt_pk_bf16_f32 v1, v10, v11
	v_cvt_pk_bf16_f32 v2, v4, v5
	v_cvt_pk_bf16_f32 v3, v6, v7
	global_store_dwordx4 v[12:13], v[0:3], off
	s_cbranch_vccz .LBB0_71
	s_waitcnt vmcnt(0)
	s_cmpk_gt_u32 s3, 0xff
	s_cbranch_scc1 .LBB0_78
	s_barrier

.LBB0_523:
	s_add_u32 s42, s30, 0xfffc0080
	s_addc_u32 s43, s31, -1
	s_add_i32 s80, 0, 0x10000
	v_add_u32_e32 v140, s80, v144
	ds_read_b128 v[146:149], v140
	ds_read_b128 v[150:153], v140 offset:1024
	ds_read_b128 v[154:157], v140 offset:2048
	ds_read_b128 v[158:161], v140 offset:3072
	s_cmp_eq_u32 s79, 12
	s_cselect_b32 s53, s45, s43
	s_cselect_b32 s52, s75, s42
	s_cselect_b32 s51, s1, s78
	s_cselect_b32 s50, s76, s77
	v_lshl_add_u64 v[140:141], s[30:31], 0, v[136:137]
	s_add_i32 m0, s58, 0xc000
	ds_read_b128 v[174:177], v145
	ds_read_b128 v[178:181], v145 offset:1024
	ds_read_b128 v[182:185], v145 offset:2048
	ds_read_b128 v[186:189], v145 offset:3072
	ds_read_b128 v[190:193], v145 offset:4096
	ds_read_b128 v[194:197], v145 offset:5120
	ds_read_b128 v[198:201], v145 offset:6144
	ds_read_b128 v[228:231], v145 offset:7168
	global_load_lds_dwordx4 v[140:141], off
	v_lshl_add_u64 v[140:141], s[30:31], 0, v[138:139]
	s_add_i32 m0, s58, 0xe000
	s_nop 0
	global_load_lds_dwordx4 v[140:141], off
	s_waitcnt lgkmcnt(8)
	s_barrier
	s_waitcnt lgkmcnt(0)
	s_setprio 1
	s_waitcnt lgkmcnt(0)
	v_mfma_f32_16x16x32_bf16 v[126:129], v[146:149], v[174:177], v[126:129]
	v_mfma_f32_16x16x32_bf16 v[114:117], v[154:157], v[174:177], v[114:117]
	v_mfma_f32_16x16x32_bf16 v[110:113], v[146:149], v[182:185], v[110:113]
	v_mfma_f32_16x16x32_bf16 v[98:101], v[154:157], v[182:185], v[98:101]
	v_mfma_f32_16x16x32_bf16 v[92:95], v[146:149], v[190:193], v[92:95]
	v_mfma_f32_16x16x32_bf16 v[80:83], v[154:157], v[190:193], v[80:83]
	v_mfma_f32_16x16x32_bf16 v[76:79], v[146:149], v[198:201], v[76:79]
	v_mfma_f32_16x16x32_bf16 v[64:67], v[154:157], v[198:201], v[64:67]
	v_mfma_f32_16x16x32_bf16 v[126:129], v[150:153], v[178:181], v[126:129]
	v_mfma_f32_16x16x32_bf16 v[114:117], v[158:161], v[178:181], v[114:117]
	v_mfma_f32_16x16x32_bf16 v[110:113], v[150:153], v[186:189], v[110:113]
	v_mfma_f32_16x16x32_bf16 v[98:101], v[158:161], v[186:189], v[98:101]
	v_mfma_f32_16x16x32_bf16 v[92:95], v[150:153], v[194:197], v[92:95]
	v_mfma_f32_16x16x32_bf16 v[80:83], v[158:161], v[194:197], v[80:83]
	v_mfma_f32_16x16x32_bf16 v[76:79], v[150:153], v[228:231], v[76:79]
	v_mfma_f32_16x16x32_bf16 v[64:67], v[158:161], v[228:231], v[64:67]
	s_setprio 0
	s_barrier
	s_add_i32 s42, 0, 0x14000
	v_add_u32_e32 v140, s42, v144
	s_add_i32 s43, s80, s37
	ds_read_b128 v[232:235], v140
	ds_read_b128 v[236:239], v140 offset:1024
	ds_read_b128 v[240:243], v140 offset:2048
	ds_read_b128 v[244:247], v140 offset:3072
	v_lshl_add_u64 v[140:141], s[50:51], 0, v[96:97]
	s_mov_b32 m0, s43
	v_lshl_add_u64 v[162:163], s[50:51], 0, v[130:131]
	global_load_lds_dwordx4 v[140:141], off
	s_add_i32 m0, s43, 0x2000
	s_nop 0
	global_load_lds_dwordx4 v[162:163], off
	s_barrier
	s_waitcnt lgkmcnt(0)
	s_setprio 1
	s_waitcnt lgkmcnt(0)
	v_mfma_f32_16x16x32_bf16 v[122:125], v[232:235], v[174:177], v[122:125]
	v_mfma_f32_16x16x32_bf16 v[118:121], v[240:243], v[174:177], v[118:121]
	v_mfma_f32_16x16x32_bf16 v[106:109], v[232:235], v[182:185], v[106:109]
	v_mfma_f32_16x16x32_bf16 v[102:105], v[240:243], v[182:185], v[102:105]
	v_mfma_f32_16x16x32_bf16 v[88:91], v[232:235], v[190:193], v[88:91]
	v_mfma_f32_16x16x32_bf16 v[84:87], v[240:243], v[190:193], v[84:87]
	v_mfma_f32_16x16x32_bf16 v[72:75], v[232:235], v[198:201], v[72:75]
	v_mfma_f32_16x16x32_bf16 v[68:71], v[240:243], v[198:201], v[68:71]
	v_mfma_f32_16x16x32_bf16 v[122:125], v[236:239], v[178:181], v[122:125]
	v_mfma_f32_16x16x32_bf16 v[118:121], v[244:247], v[178:181], v[118:121]
	v_mfma_f32_16x16x32_bf16 v[106:109], v[236:239], v[186:189], v[106:109]
	v_mfma_f32_16x16x32_bf16 v[102:105], v[244:247], v[186:189], v[102:105]
	v_mfma_f32_16x16x32_bf16 v[88:91], v[236:239], v[194:197], v[88:91]
	v_mfma_f32_16x16x32_bf16 v[84:87], v[244:247], v[194:197], v[84:87]
	v_mfma_f32_16x16x32_bf16 v[72:75], v[236:239], v[228:231], v[72:75]
	v_mfma_f32_16x16x32_bf16 v[68:71], v[244:247], v[228:231], v[68:71]
	s_setprio 0
	s_mov_b32 m0, s58
	v_lshl_add_u64 v[166:167], s[52:53], 0, v[134:135]
	s_barrier
	ds_read_b128 v[174:177], v145 offset:16384
	ds_read_b128 v[178:181], v145 offset:17408
	ds_read_b128 v[182:185], v145 offset:18432
	ds_read_b128 v[186:189], v145 offset:19456
	ds_read_b128 v[190:193], v145 offset:20480
	ds_read_b128 v[194:197], v145 offset:21504
	ds_read_b128 v[198:201], v145 offset:22528
	ds_read_b128 v[228:231], v145 offset:23552
	global_load_lds_dwordx4 v[166:167], off
	v_lshl_add_u64 v[168:169], s[52:53], 0, v[132:133]
	s_mov_b32 m0, s59
	s_nop 0
	global_load_lds_dwordx4 v[168:169], off
	s_barrier
	s_waitcnt lgkmcnt(0)
	s_setprio 1
	s_waitcnt lgkmcnt(0)
	v_mfma_f32_16x16x32_bf16 v[60:63], v[146:149], v[174:177], v[60:63]
	v_mfma_f32_16x16x32_bf16 v[48:51], v[154:157], v[174:177], v[48:51]
	v_mfma_f32_16x16x32_bf16 v[44:47], v[146:149], v[182:185], v[44:47]
	v_mfma_f32_16x16x32_bf16 v[32:35], v[154:157], v[182:185], v[32:35]
	v_mfma_f32_16x16x32_bf16 v[28:31], v[146:149], v[190:193], v[28:31]
	v_mfma_f32_16x16x32_bf16 v[16:19], v[154:157], v[190:193], v[16:19]
	v_mfma_f32_16x16x32_bf16 v[12:15], v[146:149], v[198:201], v[12:15]
	v_mfma_f32_16x16x32_bf16 v[4:7], v[154:157], v[198:201], v[4:7]
	v_mfma_f32_16x16x32_bf16 v[60:63], v[150:153], v[178:181], v[60:63]
	v_mfma_f32_16x16x32_bf16 v[48:51], v[158:161], v[178:181], v[48:51]
	v_mfma_f32_16x16x32_bf16 v[44:47], v[150:153], v[186:189], v[44:47]
	v_mfma_f32_16x16x32_bf16 v[32:35], v[158:161], v[186:189], v[32:35]
	v_mfma_f32_16x16x32_bf16 v[28:31], v[150:153], v[194:197], v[28:31]
	v_mfma_f32_16x16x32_bf16 v[16:19], v[158:161], v[194:197], v[16:19]
	v_mfma_f32_16x16x32_bf16 v[12:15], v[150:153], v[228:231], v[12:15]
	v_mfma_f32_16x16x32_bf16 v[4:7], v[158:161], v[228:231], v[4:7]
	s_setprio 0
	s_barrier
	s_add_u32 s80, s50, 0x40000
	s_addc_u32 s81, s51, 0
	s_add_i32 s42, s42, s37
	v_lshl_add_u64 v[146:147], s[80:81], 0, v[96:97]
	s_mov_b32 m0, s42
	s_nop 0
	global_load_lds_dwordx4 v[146:147], off
	v_lshl_add_u64 v[146:147], s[80:81], 0, v[130:131]
	s_add_i32 m0, s42, 0x2000
	s_nop 0
	global_load_lds_dwordx4 v[146:147], off
	s_waitcnt vmcnt(6)
	s_barrier
	s_setprio 1
	v_mfma_f32_16x16x32_bf16 v[56:59], v[232:235], v[174:177], v[56:59]
	v_mfma_f32_16x16x32_bf16 v[52:55], v[240:243], v[174:177], v[52:55]
	v_mfma_f32_16x16x32_bf16 v[40:43], v[232:235], v[182:185], v[40:43]
	v_mfma_f32_16x16x32_bf16 v[36:39], v[240:243], v[182:185], v[36:39]
	v_mfma_f32_16x16x32_bf16 v[24:27], v[232:235], v[190:193], v[24:27]
	v_mfma_f32_16x16x32_bf16 v[20:23], v[240:243], v[190:193], v[20:23]
	v_mfma_f32_16x16x32_bf16 v[8:11], v[232:235], v[198:201], v[8:11]
	v_mfma_f32_16x16x32_bf16 v[0:3], v[240:243], v[198:201], v[0:3]
	v_mfma_f32_16x16x32_bf16 v[56:59], v[236:239], v[178:181], v[56:59]
	v_mfma_f32_16x16x32_bf16 v[52:55], v[244:247], v[178:181], v[52:55]
	v_mfma_f32_16x16x32_bf16 v[40:43], v[236:239], v[186:189], v[40:43]
	v_mfma_f32_16x16x32_bf16 v[36:39], v[244:247], v[186:189], v[36:39]
	v_mfma_f32_16x16x32_bf16 v[24:27], v[236:239], v[194:197], v[24:27]
	v_mfma_f32_16x16x32_bf16 v[20:23], v[244:247], v[194:197], v[20:23]
	v_mfma_f32_16x16x32_bf16 v[8:11], v[236:239], v[228:231], v[8:11]
	v_mfma_f32_16x16x32_bf16 v[0:3], v[244:247], v[228:231], v[0:3]
	s_setprio 0
	s_add_i32 s42, 0, 0x18000
	v_add_u32_e32 v158, s42, v144
	s_barrier
	ds_read_b128 v[146:149], v158
	ds_read_b128 v[150:153], v158 offset:1024
	ds_read_b128 v[154:157], v158 offset:2048
	ds_read_b128 v[158:161], v158 offset:3072
	s_add_u32 s52, s52, 0x40000
	s_addc_u32 s53, s53, 0
	s_mov_b32 m0, s60
	v_lshl_add_u64 v[202:203], s[52:53], 0, v[134:135]
	ds_read_b128 v[174:177], v145 offset:32768
	ds_read_b128 v[178:181], v145 offset:33792
	ds_read_b128 v[182:185], v145 offset:34816
	ds_read_b128 v[186:189], v145 offset:35840
	ds_read_b128 v[190:193], v145 offset:36864
	ds_read_b128 v[194:197], v145 offset:37888
	ds_read_b128 v[198:201], v145 offset:38912
	ds_read_b128 v[228:231], v145 offset:39936
	global_load_lds_dwordx4 v[202:203], off
	v_lshl_add_u64 v[202:203], s[52:53], 0, v[132:133]
	s_mov_b32 m0, s61
	s_nop 0
	global_load_lds_dwordx4 v[202:203], off
	s_waitcnt lgkmcnt(8)
	s_barrier
	s_waitcnt lgkmcnt(0)
	s_setprio 1
	s_waitcnt lgkmcnt(0)
	v_mfma_f32_16x16x32_bf16 v[126:129], v[146:149], v[174:177], v[126:129]
	v_mfma_f32_16x16x32_bf16 v[114:117], v[154:157], v[174:177], v[114:117]
	v_mfma_f32_16x16x32_bf16 v[110:113], v[146:149], v[182:185], v[110:113]
	v_mfma_f32_16x16x32_bf16 v[98:101], v[154:157], v[182:185], v[98:101]
	v_mfma_f32_16x16x32_bf16 v[92:95], v[146:149], v[190:193], v[92:95]
	v_mfma_f32_16x16x32_bf16 v[80:83], v[154:157], v[190:193], v[80:83]
	v_mfma_f32_16x16x32_bf16 v[76:79], v[146:149], v[198:201], v[76:79]
	v_mfma_f32_16x16x32_bf16 v[64:67], v[154:157], v[198:201], v[64:67]
	v_mfma_f32_16x16x32_bf16 v[126:129], v[150:153], v[178:181], v[126:129]
	v_mfma_f32_16x16x32_bf16 v[114:117], v[158:161], v[178:181], v[114:117]
	v_mfma_f32_16x16x32_bf16 v[110:113], v[150:153], v[186:189], v[110:113]
	v_mfma_f32_16x16x32_bf16 v[98:101], v[158:161], v[186:189], v[98:101]
	v_mfma_f32_16x16x32_bf16 v[92:95], v[150:153], v[194:197], v[92:95]
	v_mfma_f32_16x16x32_bf16 v[80:83], v[158:161], v[194:197], v[80:83]
	v_mfma_f32_16x16x32_bf16 v[76:79], v[150:153], v[228:231], v[76:79]
	v_mfma_f32_16x16x32_bf16 v[64:67], v[158:161], v[228:231], v[64:67]
	s_setprio 0
	s_barrier
	s_add_i32 s43, 0, 0x1c000
	s_add_i32 s42, s42, s37
	v_add_u32_e32 v164, s43, v144
	v_lshl_add_u64 v[140:141], v[140:141], 0, s[56:57]
	s_mov_b32 m0, s42
	ds_read_b128 v[232:235], v164
	ds_read_b128 v[236:239], v164 offset:1024
	ds_read_b128 v[240:243], v164 offset:2048
	ds_read_b128 v[244:247], v164 offset:3072
	global_load_lds_dwordx4 v[140:141], off
	v_lshl_add_u64 v[140:141], v[162:163], 0, s[56:57]
	s_add_i32 m0, s42, 0x2000
	s_nop 0
	global_load_lds_dwordx4 v[140:141], off
	s_barrier
	s_waitcnt lgkmcnt(0)
	s_setprio 1
	s_waitcnt lgkmcnt(0)
	v_mfma_f32_16x16x32_bf16 v[122:125], v[232:235], v[174:177], v[122:125]
	v_mfma_f32_16x16x32_bf16 v[118:121], v[240:243], v[174:177], v[118:121]
	v_mfma_f32_16x16x32_bf16 v[106:109], v[232:235], v[182:185], v[106:109]
	v_mfma_f32_16x16x32_bf16 v[102:105], v[240:243], v[182:185], v[102:105]
	v_mfma_f32_16x16x32_bf16 v[88:91], v[232:235], v[190:193], v[88:91]
	v_mfma_f32_16x16x32_bf16 v[84:87], v[240:243], v[190:193], v[84:87]
	v_mfma_f32_16x16x32_bf16 v[72:75], v[232:235], v[198:201], v[72:75]
	v_mfma_f32_16x16x32_bf16 v[68:71], v[240:243], v[198:201], v[68:71]
	v_mfma_f32_16x16x32_bf16 v[122:125], v[236:239], v[178:181], v[122:125]
	v_mfma_f32_16x16x32_bf16 v[118:121], v[244:247], v[178:181], v[118:121]
	v_mfma_f32_16x16x32_bf16 v[106:109], v[236:239], v[186:189], v[106:109]
	v_mfma_f32_16x16x32_bf16 v[102:105], v[244:247], v[186:189], v[102:105]
	v_mfma_f32_16x16x32_bf16 v[88:91], v[236:239], v[194:197], v[88:91]
	v_mfma_f32_16x16x32_bf16 v[84:87], v[244:247], v[194:197], v[84:87]
	v_mfma_f32_16x16x32_bf16 v[72:75], v[236:239], v[228:231], v[72:75]
	v_mfma_f32_16x16x32_bf16 v[68:71], v[244:247], v[228:231], v[68:71]
	s_setprio 0
	s_mov_b32 m0, s70
	v_lshl_add_u64 v[140:141], v[166:167], 0, s[56:57]
	s_barrier
	ds_read_b128 v[174:177], v145 offset:49152
	ds_read_b128 v[178:181], v145 offset:50176
	ds_read_b128 v[182:185], v145 offset:51200
	ds_read_b128 v[186:189], v145 offset:52224
	ds_read_b128 v[190:193], v145 offset:53248
	ds_read_b128 v[194:197], v145 offset:54272
	ds_read_b128 v[198:201], v145 offset:55296
	ds_read_b128 v[228:231], v145 offset:56320
	global_load_lds_dwordx4 v[140:141], off
	v_lshl_add_u64 v[140:141], v[168:169], 0, s[56:57]
	s_mov_b32 m0, s71
	s_nop 0
	global_load_lds_dwordx4 v[140:141], off
	s_barrier
	s_waitcnt lgkmcnt(0)
	s_setprio 1
	s_waitcnt lgkmcnt(0)
	v_mfma_f32_16x16x32_bf16 v[60:63], v[146:149], v[174:177], v[60:63]
	v_mfma_f32_16x16x32_bf16 v[48:51], v[154:157], v[174:177], v[48:51]
	v_mfma_f32_16x16x32_bf16 v[44:47], v[146:149], v[182:185], v[44:47]
	v_mfma_f32_16x16x32_bf16 v[32:35], v[154:157], v[182:185], v[32:35]
	v_mfma_f32_16x16x32_bf16 v[28:31], v[146:149], v[190:193], v[28:31]
	v_mfma_f32_16x16x32_bf16 v[16:19], v[154:157], v[190:193], v[16:19]
	v_mfma_f32_16x16x32_bf16 v[12:15], v[146:149], v[198:201], v[12:15]
	v_mfma_f32_16x16x32_bf16 v[4:7], v[154:157], v[198:201], v[4:7]
	v_mfma_f32_16x16x32_bf16 v[60:63], v[150:153], v[178:181], v[60:63]
	v_mfma_f32_16x16x32_bf16 v[48:51], v[158:161], v[178:181], v[48:51]
	v_mfma_f32_16x16x32_bf16 v[44:47], v[150:153], v[186:189], v[44:47]
	v_mfma_f32_16x16x32_bf16 v[32:35], v[158:161], v[186:189], v[32:35]
	v_mfma_f32_16x16x32_bf16 v[28:31], v[150:153], v[194:197], v[28:31]
	v_mfma_f32_16x16x32_bf16 v[16:19], v[158:161], v[194:197], v[16:19]
	v_mfma_f32_16x16x32_bf16 v[12:15], v[150:153], v[228:231], v[12:15]
	v_mfma_f32_16x16x32_bf16 v[4:7], v[158:161], v[228:231], v[4:7]
	s_setprio 0
	s_barrier
	s_add_u32 s50, s50, 0x40080
	s_addc_u32 s51, s51, 0
	s_add_i32 s42, s43, s37
	v_lshl_add_u64 v[140:141], s[50:51], 0, v[96:97]
	s_mov_b32 m0, s42
	s_nop 0
	global_load_lds_dwordx4 v[140:141], off
	v_lshl_add_u64 v[140:141], s[50:51], 0, v[130:131]
	s_add_i32 m0, s42, 0x2000
	s_nop 0
	global_load_lds_dwordx4 v[140:141], off
	s_waitcnt vmcnt(6)
	s_barrier
	s_setprio 1
	v_mfma_f32_16x16x32_bf16 v[56:59], v[232:235], v[174:177], v[56:59]
	v_mfma_f32_16x16x32_bf16 v[52:55], v[240:243], v[174:177], v[52:55]
	v_mfma_f32_16x16x32_bf16 v[40:43], v[232:235], v[182:185], v[40:43]
	v_mfma_f32_16x16x32_bf16 v[36:39], v[240:243], v[182:185], v[36:39]
	v_mfma_f32_16x16x32_bf16 v[24:27], v[232:235], v[190:193], v[24:27]
	v_mfma_f32_16x16x32_bf16 v[20:23], v[240:243], v[190:193], v[20:23]
	v_mfma_f32_16x16x32_bf16 v[8:11], v[232:235], v[198:201], v[8:11]
	v_mfma_f32_16x16x32_bf16 v[0:3], v[240:243], v[198:201], v[0:3]
	v_mfma_f32_16x16x32_bf16 v[56:59], v[236:239], v[178:181], v[56:59]
	v_mfma_f32_16x16x32_bf16 v[52:55], v[244:247], v[178:181], v[52:55]
	v_mfma_f32_16x16x32_bf16 v[40:43], v[236:239], v[186:189], v[40:43]
	v_mfma_f32_16x16x32_bf16 v[36:39], v[244:247], v[186:189], v[36:39]
	v_mfma_f32_16x16x32_bf16 v[24:27], v[236:239], v[194:197], v[24:27]
	v_mfma_f32_16x16x32_bf16 v[20:23], v[244:247], v[194:197], v[20:23]
	v_mfma_f32_16x16x32_bf16 v[8:11], v[236:239], v[228:231], v[8:11]
	v_mfma_f32_16x16x32_bf16 v[0:3], v[244:247], v[228:231], v[0:3]
	s_setprio 0
	s_add_i32 s79, s79, 2
	s_add_u32 s30, s30, 0x100
	s_addc_u32 s31, s31, 0
	s_add_u32 s77, s77, 0x100
	s_addc_u32 s78, s78, 0
	s_cmp_gt_u32 s79, 13
	s_barrier
	s_cbranch_scc0 .LBB0_523
	v_mov_b32_e32 v174, 0xbfb8aa3b
	v_mul_f32_e32 v147, 0xbfb8aa3b, v126
	v_exp_f32_e32 v147, v147
	v_pk_mul_f32 v[122:123], v[126:127], v[122:123]
	v_mul_f32_e32 v126, 0xbfb8aa3b, v128
	v_exp_f32_e32 v126, v126
	v_add_f32_e32 v147, 1.0, v147
	v_rcp_f32_e32 v152, v147
	v_mul_f32_e32 v147, 0xbfb8aa3b, v127
	v_mul_f32_e32 v127, 0xbfb8aa3b, v129
	v_exp_f32_e32 v127, v127
	v_add_f32_e32 v126, 1.0, v126
	v_rcp_f32_e32 v126, v126
	v_pk_mul_f32 v[124:125], v[128:129], v[124:125]
	v_add_f32_e32 v127, 1.0, v127
	v_rcp_f32_e32 v127, v127
	v_exp_f32_e32 v147, v147
	s_lshl_b32 s30, s73, 7
	v_mov_b32_e32 v140, v143
	v_pk_mul_f32 v[124:125], v[126:127], v[124:125]
	v_pk_mul_f32 v[126:127], v[114:115], v[174:175] op_sel_hi:[1,0]
	v_exp_f32_e32 v126, v126
	v_exp_f32_e32 v127, v127
	v_pk_mul_f32 v[114:115], v[114:115], v[118:119]
	v_add_f32_e32 v147, 1.0, v147
	v_pk_add_f32 v[126:127], v[126:127], 1.0 op_sel_hi:[1,0]
	v_rcp_f32_e32 v126, v126
	v_rcp_f32_e32 v127, v127
	v_mov_b32_e32 v141, v142
	s_or_b32 s30, s30, s69
	v_rcp_f32_e32 v153, v147
	v_pk_mul_f32 v[118:119], v[126:127], v[114:115]
	v_pk_mul_f32 v[114:115], v[116:117], v[174:175] op_sel_hi:[1,0]
	v_exp_f32_e32 v114, v114
	v_exp_f32_e32 v115, v115
	s_lshl_b32 s1, s74, 8
	v_pk_add_f32 v[114:115], v[114:115], 1.0 op_sel_hi:[1,0]
	v_rcp_f32_e32 v114, v114
	v_rcp_f32_e32 v115, v115
	v_lshl_add_u32 v148, v140, 3, s30
	v_readlane_b32 s30, v254, 11
	s_add_i32 s1, s1, s68
	v_readlane_b32 s31, v254, 12
	v_add_u32_e32 v146, s1, v141
	v_ashrrev_i32_e32 v149, 31, v148
	v_mov_b64_e32 v[140:141], s[30:31]
	s_movk_i32 s1, 0x1600
	v_pk_mul_f32 v[120:121], v[116:117], v[120:121]
	v_mad_i64_i32 v[150:151], s[30:31], v146, s1, v[140:141]
	v_pk_mul_f32 v[122:123], v[152:153], v[122:123]
	v_pk_mul_f32 v[120:121], v[114:115], v[120:121]
	v_lshlrev_b64 v[114:115], 1, v[148:149]
	v_lshl_add_u64 v[126:127], v[150:151], 0, v[114:115]
	v_cvt_pk_bf16_f32 v116, v122, v123
	v_cvt_pk_bf16_f32 v117, v124, v125
	v_cvt_pk_bf16_f32 v118, v118, v119
	v_cvt_pk_bf16_f32 v119, v120, v121
	global_store_dwordx4 v[126:127], v[116:119], off
	v_pk_mul_f32 v[106:107], v[110:111], v[106:107]
	v_pk_mul_f32 v[108:109], v[112:113], v[108:109]
	v_pk_mul_f32 v[118:119], v[110:111], v[174:175] op_sel_hi:[1,0]
	v_pk_mul_f32 v[110:111], v[112:113], v[174:175] op_sel_hi:[1,0]
	v_exp_f32_e32 v110, v110
	v_exp_f32_e32 v111, v111
	v_exp_f32_e32 v118, v118
	v_exp_f32_e32 v119, v119
	v_pk_add_f32 v[110:111], v[110:111], 1.0 op_sel_hi:[1,0]
	v_rcp_f32_e32 v110, v110
	v_rcp_f32_e32 v111, v111
	v_pk_add_f32 v[118:119], v[118:119], 1.0 op_sel_hi:[1,0]
	v_rcp_f32_e32 v118, v118
	v_pk_mul_f32 v[108:109], v[110:111], v[108:109]
	v_pk_mul_f32 v[110:111], v[98:99], v[174:175] op_sel_hi:[1,0]
	v_exp_f32_e32 v110, v110
	v_exp_f32_e32 v111, v111
	v_pk_mul_f32 v[98:99], v[98:99], v[102:103]
	v_rcp_f32_e32 v119, v119
	v_pk_add_f32 v[110:111], v[110:111], 1.0 op_sel_hi:[1,0]
	v_rcp_f32_e32 v110, v110
	v_rcp_f32_e32 v111, v111
	v_add_u32_e32 v116, 16, v146
	v_pk_mul_f32 v[104:105], v[100:101], v[104:105]
	v_mad_i64_i32 v[116:117], s[30:31], v116, s1, v[140:141]
	v_pk_mul_f32 v[102:103], v[110:111], v[98:99]
	v_pk_mul_f32 v[98:99], v[100:101], v[174:175] op_sel_hi:[1,0]
	v_exp_f32_e32 v98, v98
	v_exp_f32_e32 v99, v99
	v_pk_mul_f32 v[106:107], v[118:119], v[106:107]
	v_lshl_add_u64 v[110:111], v[116:117], 0, v[114:115]
	v_pk_add_f32 v[98:99], v[98:99], 1.0 op_sel_hi:[1,0]
	v_rcp_f32_e32 v98, v98
	v_rcp_f32_e32 v99, v99
	v_cvt_pk_bf16_f32 v100, v102, v103
	v_pk_mul_f32 v[88:89], v[92:93], v[88:89]
	v_pk_mul_f32 v[90:91], v[94:95], v[90:91]
	v_pk_mul_f32 v[104:105], v[98:99], v[104:105]
	v_cvt_pk_bf16_f32 v98, v106, v107
	v_cvt_pk_bf16_f32 v99, v108, v109
	v_cvt_pk_bf16_f32 v101, v104, v105
	global_store_dwordx4 v[110:111], v[98:101], off
	v_pk_mul_f32 v[86:87], v[82:83], v[86:87]
	v_pk_mul_f32 v[72:73], v[76:77], v[72:73]
	v_pk_mul_f32 v[100:101], v[92:93], v[174:175] op_sel_hi:[1,0]
	v_pk_mul_f32 v[92:93], v[94:95], v[174:175] op_sel_hi:[1,0]
	v_exp_f32_e32 v92, v92
	v_exp_f32_e32 v93, v93
	v_exp_f32_e32 v100, v100
	v_exp_f32_e32 v101, v101
	v_pk_add_f32 v[92:93], v[92:93], 1.0 op_sel_hi:[1,0]
	v_rcp_f32_e32 v92, v92
	v_rcp_f32_e32 v93, v93
	v_pk_add_f32 v[100:101], v[100:101], 1.0 op_sel_hi:[1,0]
	v_rcp_f32_e32 v100, v100
	v_pk_mul_f32 v[90:91], v[92:93], v[90:91]
	v_pk_mul_f32 v[92:93], v[80:81], v[174:175] op_sel_hi:[1,0]
	v_exp_f32_e32 v92, v92
	v_exp_f32_e32 v93, v93
	v_pk_mul_f32 v[80:81], v[80:81], v[84:85]
	v_rcp_f32_e32 v101, v101
	v_pk_add_f32 v[92:93], v[92:93], 1.0 op_sel_hi:[1,0]
	v_rcp_f32_e32 v92, v92
	v_rcp_f32_e32 v93, v93
	v_add_u32_e32 v98, 32, v146
	v_mad_i64_i32 v[98:99], s[30:31], v98, s1, v[140:141]
	v_pk_mul_f32 v[84:85], v[92:93], v[80:81]
	v_pk_mul_f32 v[80:81], v[82:83], v[174:175] op_sel_hi:[1,0]
	v_exp_f32_e32 v80, v80
	v_exp_f32_e32 v81, v81
	v_pk_mul_f32 v[88:89], v[100:101], v[88:89]
	v_lshl_add_u64 v[92:93], v[98:99], 0, v[114:115]
	v_pk_add_f32 v[80:81], v[80:81], 1.0 op_sel_hi:[1,0]
	v_rcp_f32_e32 v80, v80
	v_rcp_f32_e32 v81, v81
	v_cvt_pk_bf16_f32 v82, v84, v85
	v_pk_mul_f32 v[74:75], v[78:79], v[74:75]
	v_pk_mul_f32 v[70:71], v[66:67], v[70:71]
	v_pk_mul_f32 v[86:87], v[80:81], v[86:87]
	v_cvt_pk_bf16_f32 v80, v88, v89
	v_cvt_pk_bf16_f32 v81, v90, v91
	v_cvt_pk_bf16_f32 v83, v86, v87
	global_store_dwordx4 v[92:93], v[80:83], off
	v_pk_mul_f32 v[56:57], v[60:61], v[56:57]
	v_pk_mul_f32 v[58:59], v[62:63], v[58:59]
	v_pk_mul_f32 v[82:83], v[76:77], v[174:175] op_sel_hi:[1,0]
	v_pk_mul_f32 v[76:77], v[78:79], v[174:175] op_sel_hi:[1,0]
	v_exp_f32_e32 v76, v76
	v_exp_f32_e32 v77, v77
	v_exp_f32_e32 v82, v82
	v_exp_f32_e32 v83, v83
	v_pk_add_f32 v[76:77], v[76:77], 1.0 op_sel_hi:[1,0]
	v_rcp_f32_e32 v76, v76
	v_rcp_f32_e32 v77, v77
	v_pk_add_f32 v[82:83], v[82:83], 1.0 op_sel_hi:[1,0]
	v_rcp_f32_e32 v82, v82
	v_pk_mul_f32 v[74:75], v[76:77], v[74:75]
	v_pk_mul_f32 v[76:77], v[64:65], v[174:175] op_sel_hi:[1,0]
	v_exp_f32_e32 v76, v76
	v_exp_f32_e32 v77, v77
	v_pk_mul_f32 v[64:65], v[64:65], v[68:69]
	v_rcp_f32_e32 v83, v83
	v_pk_add_f32 v[76:77], v[76:77], 1.0 op_sel_hi:[1,0]
	v_rcp_f32_e32 v76, v76
	v_rcp_f32_e32 v77, v77
	v_add_u32_e32 v80, 48, v146
	v_mad_i64_i32 v[80:81], s[30:31], v80, s1, v[140:141]
	v_pk_mul_f32 v[68:69], v[76:77], v[64:65]
	v_pk_mul_f32 v[64:65], v[66:67], v[174:175] op_sel_hi:[1,0]
	v_exp_f32_e32 v64, v64
	v_exp_f32_e32 v65, v65
	v_pk_mul_f32 v[72:73], v[82:83], v[72:73]
	v_lshl_add_u64 v[76:77], v[80:81], 0, v[114:115]
	v_pk_add_f32 v[64:65], v[64:65], 1.0 op_sel_hi:[1,0]
	v_rcp_f32_e32 v64, v64
	v_rcp_f32_e32 v65, v65
	v_cvt_pk_bf16_f32 v66, v68, v69
	v_pk_mul_f32 v[54:55], v[50:51], v[54:55]
	v_pk_mul_f32 v[40:41], v[44:45], v[40:41]
	v_pk_mul_f32 v[70:71], v[64:65], v[70:71]
	v_cvt_pk_bf16_f32 v64, v72, v73
	v_cvt_pk_bf16_f32 v65, v74, v75
	v_cvt_pk_bf16_f32 v67, v70, v71
	global_store_dwordx4 v[76:77], v[64:67], off
	v_pk_mul_f32 v[42:43], v[46:47], v[42:43]
	v_pk_mul_f32 v[38:39], v[34:35], v[38:39]
	v_pk_mul_f32 v[66:67], v[60:61], v[174:175] op_sel_hi:[1,0]
	v_pk_mul_f32 v[60:61], v[62:63], v[174:175] op_sel_hi:[1,0]
	v_exp_f32_e32 v60, v60
	v_exp_f32_e32 v61, v61
	v_exp_f32_e32 v66, v66
	v_exp_f32_e32 v67, v67
	v_pk_add_f32 v[60:61], v[60:61], 1.0 op_sel_hi:[1,0]
	v_rcp_f32_e32 v60, v60
	v_rcp_f32_e32 v61, v61
	v_pk_add_f32 v[66:67], v[66:67], 1.0 op_sel_hi:[1,0]
	v_rcp_f32_e32 v66, v66
	v_pk_mul_f32 v[58:59], v[60:61], v[58:59]
	v_pk_mul_f32 v[60:61], v[48:49], v[174:175] op_sel_hi:[1,0]
	v_exp_f32_e32 v60, v60
	v_exp_f32_e32 v61, v61
	v_pk_mul_f32 v[48:49], v[48:49], v[52:53]
	v_rcp_f32_e32 v67, v67
	v_pk_add_f32 v[60:61], v[60:61], 1.0 op_sel_hi:[1,0]
	v_rcp_f32_e32 v60, v60
	v_rcp_f32_e32 v61, v61
	v_add_u32_e32 v64, 0x80, v146
	v_mad_i64_i32 v[64:65], s[30:31], v64, s1, v[140:141]
	v_pk_mul_f32 v[52:53], v[60:61], v[48:49]
	v_pk_mul_f32 v[48:49], v[50:51], v[174:175] op_sel_hi:[1,0]
	v_exp_f32_e32 v48, v48
	v_exp_f32_e32 v49, v49
	v_pk_mul_f32 v[56:57], v[66:67], v[56:57]
	v_lshl_add_u64 v[60:61], v[64:65], 0, v[114:115]
	v_pk_add_f32 v[48:49], v[48:49], 1.0 op_sel_hi:[1,0]
	v_rcp_f32_e32 v48, v48
	v_rcp_f32_e32 v49, v49
	v_cvt_pk_bf16_f32 v50, v52, v53
	v_pk_mul_f32 v[24:25], v[28:29], v[24:25]
	v_pk_mul_f32 v[26:27], v[30:31], v[26:27]
	v_pk_mul_f32 v[54:55], v[48:49], v[54:55]
	v_cvt_pk_bf16_f32 v48, v56, v57
	v_cvt_pk_bf16_f32 v49, v58, v59
	v_cvt_pk_bf16_f32 v51, v54, v55
	global_store_dwordx4 v[60:61], v[48:51], off
	v_pk_mul_f32 v[22:23], v[18:19], v[22:23]
	v_pk_mul_f32 v[8:9], v[12:13], v[8:9]
	v_pk_mul_f32 v[50:51], v[44:45], v[174:175] op_sel_hi:[1,0]
	v_pk_mul_f32 v[44:45], v[46:47], v[174:175] op_sel_hi:[1,0]
	v_exp_f32_e32 v44, v44
	v_exp_f32_e32 v45, v45
	v_exp_f32_e32 v50, v50
	v_exp_f32_e32 v51, v51
	v_pk_add_f32 v[44:45], v[44:45], 1.0 op_sel_hi:[1,0]
	v_rcp_f32_e32 v44, v44
	v_rcp_f32_e32 v45, v45
	v_pk_add_f32 v[50:51], v[50:51], 1.0 op_sel_hi:[1,0]
	v_rcp_f32_e32 v50, v50
	v_pk_mul_f32 v[42:43], v[44:45], v[42:43]
	v_pk_mul_f32 v[44:45], v[32:33], v[174:175] op_sel_hi:[1,0]
	v_exp_f32_e32 v44, v44
	v_exp_f32_e32 v45, v45
	v_pk_mul_f32 v[32:33], v[32:33], v[36:37]
	v_rcp_f32_e32 v51, v51
	v_pk_add_f32 v[44:45], v[44:45], 1.0 op_sel_hi:[1,0]
	v_rcp_f32_e32 v44, v44
	v_rcp_f32_e32 v45, v45
	v_add_u32_e32 v48, 0x90, v146
	v_mad_i64_i32 v[48:49], s[30:31], v48, s1, v[140:141]
	v_pk_mul_f32 v[36:37], v[44:45], v[32:33]
	v_pk_mul_f32 v[32:33], v[34:35], v[174:175] op_sel_hi:[1,0]
	v_exp_f32_e32 v32, v32
	v_exp_f32_e32 v33, v33
	v_pk_mul_f32 v[40:41], v[50:51], v[40:41]
	v_lshl_add_u64 v[44:45], v[48:49], 0, v[114:115]
	v_pk_add_f32 v[32:33], v[32:33], 1.0 op_sel_hi:[1,0]
	v_rcp_f32_e32 v32, v32
	v_rcp_f32_e32 v33, v33
	v_cvt_pk_bf16_f32 v34, v36, v37
	v_pk_mul_f32 v[10:11], v[14:15], v[10:11]
	v_pk_mul_f32 v[0:1], v[4:5], v[0:1]
	v_pk_mul_f32 v[38:39], v[32:33], v[38:39]
	v_cvt_pk_bf16_f32 v32, v40, v41
	v_cvt_pk_bf16_f32 v33, v42, v43
	v_cvt_pk_bf16_f32 v35, v38, v39
	global_store_dwordx4 v[44:45], v[32:35], off
	v_pk_mul_f32 v[2:3], v[6:7], v[2:3]
	s_and_b64 vcc, exec, s[40:41]
	v_pk_mul_f32 v[34:35], v[28:29], v[174:175] op_sel_hi:[1,0]
	v_pk_mul_f32 v[28:29], v[30:31], v[174:175] op_sel_hi:[1,0]
	v_exp_f32_e32 v28, v28
	v_exp_f32_e32 v29, v29
	v_exp_f32_e32 v34, v34
	v_exp_f32_e32 v35, v35
	v_pk_add_f32 v[28:29], v[28:29], 1.0 op_sel_hi:[1,0]
	v_rcp_f32_e32 v28, v28
	v_rcp_f32_e32 v29, v29
	v_pk_add_f32 v[34:35], v[34:35], 1.0 op_sel_hi:[1,0]
	v_rcp_f32_e32 v34, v34
	v_pk_mul_f32 v[26:27], v[28:29], v[26:27]
	v_pk_mul_f32 v[28:29], v[16:17], v[174:175] op_sel_hi:[1,0]
	v_exp_f32_e32 v28, v28
	v_exp_f32_e32 v29, v29
	v_pk_mul_f32 v[16:17], v[16:17], v[20:21]
	v_rcp_f32_e32 v35, v35
	v_pk_add_f32 v[28:29], v[28:29], 1.0 op_sel_hi:[1,0]
	v_rcp_f32_e32 v28, v28
	v_rcp_f32_e32 v29, v29
	v_add_u32_e32 v32, 0xa0, v146
	v_mad_i64_i32 v[32:33], s[30:31], v32, s1, v[140:141]
	v_pk_mul_f32 v[20:21], v[28:29], v[16:17]
	v_pk_mul_f32 v[16:17], v[18:19], v[174:175] op_sel_hi:[1,0]
	v_exp_f32_e32 v16, v16
	v_exp_f32_e32 v17, v17
	v_pk_mul_f32 v[24:25], v[34:35], v[24:25]
	v_lshl_add_u64 v[28:29], v[32:33], 0, v[114:115]
	v_pk_add_f32 v[16:17], v[16:17], 1.0 op_sel_hi:[1,0]
	v_rcp_f32_e32 v16, v16
	v_rcp_f32_e32 v17, v17
	v_cvt_pk_bf16_f32 v18, v20, v21
	s_mov_b32 s73, s0
	s_mov_b32 s74, s44
	v_pk_mul_f32 v[22:23], v[16:17], v[22:23]
	v_cvt_pk_bf16_f32 v16, v24, v25
	v_cvt_pk_bf16_f32 v17, v26, v27
	v_cvt_pk_bf16_f32 v19, v22, v23
	global_store_dwordx4 v[28:29], v[16:19], off
	s_mov_b64 s[50:51], s[48:49]
	s_nop 0
	v_pk_mul_f32 v[18:19], v[12:13], v[174:175] op_sel_hi:[1,0]
	v_pk_mul_f32 v[12:13], v[14:15], v[174:175] op_sel_hi:[1,0]
	v_exp_f32_e32 v12, v12
	v_exp_f32_e32 v13, v13
	v_exp_f32_e32 v18, v18
	v_exp_f32_e32 v19, v19
	v_pk_add_f32 v[12:13], v[12:13], 1.0 op_sel_hi:[1,0]
	v_rcp_f32_e32 v12, v12
	v_rcp_f32_e32 v13, v13
	v_pk_add_f32 v[18:19], v[18:19], 1.0 op_sel_hi:[1,0]
	v_rcp_f32_e32 v18, v18
	v_pk_mul_f32 v[10:11], v[12:13], v[10:11]
	v_pk_mul_f32 v[12:13], v[4:5], v[174:175] op_sel_hi:[1,0]
	v_exp_f32_e32 v12, v12
	v_exp_f32_e32 v13, v13
	v_rcp_f32_e32 v19, v19
	v_add_u32_e32 v16, 0xb0, v146
	v_pk_add_f32 v[12:13], v[12:13], 1.0 op_sel_hi:[1,0]
	v_rcp_f32_e32 v12, v12
	v_rcp_f32_e32 v13, v13
	v_mad_i64_i32 v[16:17], s[30:31], v16, s1, v[140:141]
	v_pk_mul_f32 v[8:9], v[18:19], v[8:9]
	v_pk_mul_f32 v[4:5], v[12:13], v[0:1]
	v_pk_mul_f32 v[0:1], v[6:7], v[174:175] op_sel_hi:[1,0]
	v_exp_f32_e32 v0, v0
	v_exp_f32_e32 v1, v1
	v_lshl_add_u64 v[12:13], v[16:17], 0, v[114:115]
	s_mov_b64 s[30:31], s[46:47]
	v_pk_add_f32 v[0:1], v[0:1], 1.0 op_sel_hi:[1,0]
	v_rcp_f32_e32 v0, v0
	v_rcp_f32_e32 v1, v1
	s_nop 0
	v_pk_mul_f32 v[6:7], v[0:1], v[2:3]
	v_cvt_pk_bf16_f32 v0, v8, v9
	v_cvt_pk_bf16_f32 v1, v10, v11
	v_cvt_pk_bf16_f32 v2, v4, v5
	v_cvt_pk_bf16_f32 v3, v6, v7
	global_store_dwordx4 v[12:13], v[0:3], off
	s_cbranch_vccz .LBB0_520
	s_waitcnt vmcnt(0)
	s_cmpk_gt_u32 s3, 0xff
	s_cbranch_scc1 .LBB0_527
	s_barrier
